# in-proj K loop: LDS-DMA issues placed ahead of the ds_read fragment reads in each load section
# speedup vs baseline: 1.0154x; 1.0004x over previous
; #define PG8_STAGE(bufoff, gbase, voff) do { _Pragma("unroll") for (int _i = 0; _i < 2; ++_i) \
;         __builtin_amdgcn_global_load_lds((const unsigned*)((const char*)(gbase) + (voff)[_i]), (LAS unsigned*)(lds + (bufoff) + ldsw + _i * 8192), 16, 0, 0); } while (0)
; #define PG8_LDA(dst, b, h) do { _Pragma("unroll") for (int m = 0; m < 4; ++m) _Pragma("unroll") for (int k = 0; k < 2; ++k) dst[m][k] = *(const LAS h8*)(lds + PG8_SA(b, h) + aoff + m * 2048 + k * 1024); } while (0)
; #define PG8_LDB(dst, b, h) do { _Pragma("unroll") for (int n = 0; n < 2; ++n) _Pragma("unroll") for (int k = 0; k < 2; ++k) dst[n][k] = *(const LAS h8*)(lds + PG8_SB(b, h) + boff + n * 2048 + k * 1024); } while (0)
; #define PG8_WAIT_L(n) asm volatile("s_waitcnt lgkmcnt(" #n ")" ::: "memory")
; #define PG8_BAR __builtin_amdgcn_s_barrier()
; #define PG8_SCHED __builtin_amdgcn_sched_barrier(0)
; template <class Epi>
; __device__ __forceinline__ void gemm_phase(LAS unsigned char* lds, const Gemm g, const StaticOrder& S, const Epi& E, const int tid) {
;     ...
;             PG8_LDB(B0, 0, 0); PG8_SCHED; PG8_LDA(At, 0, 0); PG8_STAGE(PG8_SA(1, 1), a1 + hstep, voffA);
;             PG8_WAIT_L(8); PG8_BAR; PG8_WAIT_L(0); PG8_MMA(0, 0, At, B0); PG8_BAR; PG8_SCHED;
;             PG8_LDB(B1, 0, 1); PG8_STAGE(PG8_SB(0, 0), b2, voffB);
;             PG8_BAR; PG8_WAIT_L(0); PG8_MMA(0, 1, At, B1); PG8_BAR;
;             PG8_LDA(At, 0, 1); PG8_STAGE(PG8_SA(0, 0), a2, voffA);
;             PG8_BAR; PG8_WAIT_L(0); PG8_MMA(1, 0, At, B0); PG8_BAR; PG8_SCHED;
.LBB0_332:
	s_add_u32 s18, s14, 0xfff80080
	s_addc_u32 s19, s15, -1
	s_add_i32 s55, 0, 0x10000
	v_add_u32_e32 v157, s55, v140
	s_cmp_eq_u32 s54, 28
	s_cselect_b32 s23, s9, s19
	s_cselect_b32 s22, s50, s18
	s_cselect_b32 s19, s1, s53
	s_cselect_b32 s18, s51, s52
	s_add_i32 m0, s39, 0xc000
	s_nop 0
	global_load_lds_dwordx4 v136, s[14:15]
	s_add_i32 m0, s39, 0xe000
	s_nop 0
	global_load_lds_dwordx4 v138, s[14:15]
	ds_read_b128 v[144:147], v157
	ds_read_b128 v[162:165], v157 offset:1024
	ds_read_b128 v[166:169], v157 offset:2048
	ds_read_b128 v[170:173], v157 offset:3072
	ds_read_b128 v[174:177], v143
	ds_read_b128 v[190:193], v143 offset:1024
	ds_read_b128 v[194:197], v143 offset:2048
	ds_read_b128 v[198:201], v143 offset:3072
	ds_read_b128 v[202:205], v143 offset:4096
	ds_read_b128 v[206:209], v143 offset:5120
	ds_read_b128 v[210:213], v143 offset:6144
	ds_read_b128 v[214:217], v143 offset:7168
	s_waitcnt lgkmcnt(8)
	s_barrier
	s_waitcnt lgkmcnt(0)
	s_waitcnt lgkmcnt(0)
	v_mfma_f32_16x16x32_bf16 v[124:127], v[144:147], v[174:177], v[124:127]
	v_mfma_f32_16x16x32_bf16 v[128:131], v[166:169], v[174:177], v[128:131]
	v_mfma_f32_16x16x32_bf16 v[108:111], v[144:147], v[194:197], v[108:111]
	v_mfma_f32_16x16x32_bf16 v[112:115], v[166:169], v[194:197], v[112:115]
	v_mfma_f32_16x16x32_bf16 v[92:95], v[144:147], v[202:205], v[92:95]
	v_mfma_f32_16x16x32_bf16 v[96:99], v[166:169], v[202:205], v[96:99]
	v_mfma_f32_16x16x32_bf16 v[76:79], v[144:147], v[210:213], v[76:79]
	v_mfma_f32_16x16x32_bf16 v[80:83], v[166:169], v[210:213], v[80:83]
	v_mfma_f32_16x16x32_bf16 v[124:127], v[162:165], v[190:193], v[124:127]
	v_mfma_f32_16x16x32_bf16 v[128:131], v[170:173], v[190:193], v[128:131]
	v_mfma_f32_16x16x32_bf16 v[108:111], v[162:165], v[198:201], v[108:111]
	v_mfma_f32_16x16x32_bf16 v[112:115], v[170:173], v[198:201], v[112:115]
	v_mfma_f32_16x16x32_bf16 v[92:95], v[162:165], v[206:209], v[92:95]
	v_mfma_f32_16x16x32_bf16 v[96:99], v[170:173], v[206:209], v[96:99]
	v_mfma_f32_16x16x32_bf16 v[76:79], v[162:165], v[214:217], v[76:79]
	v_mfma_f32_16x16x32_bf16 v[80:83], v[170:173], v[214:217], v[80:83]
	s_barrier
	s_add_i32 s58, 0, 0x14000
	s_add_i32 s55, s55, s38
	v_add_u32_e32 v157, s58, v140
	v_lshl_add_u64 v[178:179], s[18:19], 0, v[2:3]
	s_mov_b32 m0, s55
	s_nop 0
	global_load_lds_dwordx4 v[178:179], off
	v_lshl_add_u64 v[234:235], s[18:19], 0, v[0:1]
	s_add_i32 m0, s55, 0x2000
	s_nop 0
	global_load_lds_dwordx4 v[234:235], off
	ds_read_b128 v[218:221], v157
	ds_read_b128 v[222:225], v157 offset:1024
	ds_read_b128 v[226:229], v157 offset:2048
	ds_read_b128 v[230:233], v157 offset:3072
	s_barrier
	s_waitcnt lgkmcnt(0)
	s_waitcnt lgkmcnt(0)
	v_mfma_f32_16x16x32_bf16 v[116:119], v[218:221], v[174:177], v[116:119]
	v_mfma_f32_16x16x32_bf16 v[120:123], v[226:229], v[174:177], v[120:123]
	v_mfma_f32_16x16x32_bf16 v[100:103], v[218:221], v[194:197], v[100:103]
	v_mfma_f32_16x16x32_bf16 v[104:107], v[226:229], v[194:197], v[104:107]
	v_mfma_f32_16x16x32_bf16 v[84:87], v[218:221], v[202:205], v[84:87]
	v_mfma_f32_16x16x32_bf16 v[88:91], v[226:229], v[202:205], v[88:91]
	v_mfma_f32_16x16x32_bf16 v[68:71], v[218:221], v[210:213], v[68:71]
	v_mfma_f32_16x16x32_bf16 v[72:75], v[226:229], v[210:213], v[72:75]
	v_mfma_f32_16x16x32_bf16 v[116:119], v[222:225], v[190:193], v[116:119]
	v_mfma_f32_16x16x32_bf16 v[120:123], v[230:233], v[190:193], v[120:123]
	v_mfma_f32_16x16x32_bf16 v[100:103], v[222:225], v[198:201], v[100:103]
	v_mfma_f32_16x16x32_bf16 v[104:107], v[230:233], v[198:201], v[104:107]
	v_mfma_f32_16x16x32_bf16 v[84:87], v[222:225], v[206:209], v[84:87]
	v_mfma_f32_16x16x32_bf16 v[88:91], v[230:233], v[206:209], v[88:91]
	v_mfma_f32_16x16x32_bf16 v[68:71], v[222:225], v[214:217], v[68:71]
	v_mfma_f32_16x16x32_bf16 v[72:75], v[230:233], v[214:217], v[72:75]
	s_mov_b32 m0, s39
	v_lshl_add_u64 v[236:237], s[22:23], 0, v[134:135]
	s_barrier
	global_load_lds_dwordx4 v[236:237], off
	v_lshl_add_u64 v[238:239], s[22:23], 0, v[132:133]
	s_mov_b32 m0, s40
	s_nop 0
	global_load_lds_dwordx4 v[238:239], off
	ds_read_b128 v[174:177], v143 offset:16384
	ds_read_b128 v[190:193], v143 offset:17408
	ds_read_b128 v[194:197], v143 offset:18432
	ds_read_b128 v[198:201], v143 offset:19456
	ds_read_b128 v[202:205], v143 offset:20480
	ds_read_b128 v[206:209], v143 offset:21504
	ds_read_b128 v[210:213], v143 offset:22528
	ds_read_b128 v[214:217], v143 offset:23552
	s_barrier
	s_waitcnt lgkmcnt(0)
	s_waitcnt lgkmcnt(0)
	v_mfma_f32_16x16x32_bf16 v[60:63], v[144:147], v[174:177], v[60:63]
	v_mfma_f32_16x16x32_bf16 v[64:67], v[166:169], v[174:177], v[64:67]
	v_mfma_f32_16x16x32_bf16 v[44:47], v[144:147], v[194:197], v[44:47]
	v_mfma_f32_16x16x32_bf16 v[48:51], v[166:169], v[194:197], v[48:51]
	v_mfma_f32_16x16x32_bf16 v[28:31], v[144:147], v[202:205], v[28:31]
	v_mfma_f32_16x16x32_bf16 v[32:35], v[166:169], v[202:205], v[32:35]
	v_mfma_f32_16x16x32_bf16 v[12:15], v[144:147], v[210:213], v[12:15]
	v_mfma_f32_16x16x32_bf16 v[16:19], v[166:169], v[210:213], v[16:19]
	v_mfma_f32_16x16x32_bf16 v[60:63], v[162:165], v[190:193], v[60:63]
	v_mfma_f32_16x16x32_bf16 v[64:67], v[170:173], v[190:193], v[64:67]
	v_mfma_f32_16x16x32_bf16 v[44:47], v[162:165], v[198:201], v[44:47]
	v_mfma_f32_16x16x32_bf16 v[48:51], v[170:173], v[198:201], v[48:51]
	v_mfma_f32_16x16x32_bf16 v[28:31], v[162:165], v[206:209], v[28:31]
	v_mfma_f32_16x16x32_bf16 v[32:35], v[170:173], v[206:209], v[32:35]
	v_mfma_f32_16x16x32_bf16 v[12:15], v[162:165], v[214:217], v[12:15]
	v_mfma_f32_16x16x32_bf16 v[16:19], v[170:173], v[214:217], v[16:19]
	s_barrier
; #define PG8_STAGE(bufoff, gbase, voff) do { _Pragma("unroll") for (int _i = 0; _i < 2; ++_i) \
;         __builtin_amdgcn_global_load_lds((const unsigned*)((const char*)(gbase) + (voff)[_i]), (LAS unsigned*)(lds + (bufoff) + ldsw + _i * 8192), 16, 0, 0); } while (0)
; #define PG8_LDA(dst, b, h) do { _Pragma("unroll") for (int m = 0; m < 4; ++m) _Pragma("unroll") for (int k = 0; k < 2; ++k) dst[m][k] = *(const LAS h8*)(lds + PG8_SA(b, h) + aoff + m * 2048 + k * 1024); } while (0)
; #define PG8_LDB(dst, b, h) do { _Pragma("unroll") for (int n = 0; n < 2; ++n) _Pragma("unroll") for (int k = 0; k < 2; ++k) dst[n][k] = *(const LAS h8*)(lds + PG8_SB(b, h) + boff + n * 2048 + k * 1024); } while (0)
; #define PG8_WAIT_V(n) asm volatile("s_waitcnt vmcnt(" #n ")" ::: "memory")
; #define PG8_WAIT_L(n) asm volatile("s_waitcnt lgkmcnt(" #n ")" ::: "memory")
; #define PG8_BAR __builtin_amdgcn_s_barrier()
; #define PG8_SCHED __builtin_amdgcn_sched_barrier(0)
; template <class Epi>
; __device__ __forceinline__ void gemm_phase(LAS unsigned char* lds, const Gemm g, const StaticOrder& S, const Epi& E, const int tid) {
;     ...
;             PG8_STAGE(PG8_SB(0, 1), b2 + hstepB, voffB);
;             PG8_WAIT_V(6); PG8_BAR; PG8_MMA(1, 1, At, B1); PG8_BAR;
;             PG8_LDB(B0, 1, 0); PG8_SCHED; PG8_LDA(At, 1, 0); PG8_STAGE(PG8_SA(0, 1), a2 + hstep, voffA);
;             PG8_WAIT_L(8); PG8_BAR; PG8_WAIT_L(0); PG8_MMA(0, 0, At, B0); PG8_BAR; PG8_SCHED;
;             PG8_LDB(B1, 1, 1); PG8_STAGE(PG8_SB(1, 0), b3, voffB);
;             PG8_BAR; PG8_WAIT_L(0); PG8_MMA(0, 1, At, B1); PG8_BAR;
;             PG8_LDA(At, 1, 1); PG8_STAGE(PG8_SA(1, 0), a3, voffA);
	s_add_u32 s56, s18, 0x20000
	s_addc_u32 s57, s19, 0
	s_add_i32 s55, s58, s38
	s_mov_b32 m0, s55
	s_nop 0
	global_load_lds_dwordx4 v2, s[56:57]
	s_add_i32 m0, s55, 0x2000
	s_nop 0
	global_load_lds_dwordx4 v0, s[56:57]
	s_waitcnt vmcnt(6)
	s_barrier
	v_mfma_f32_16x16x32_bf16 v[52:55], v[218:221], v[174:177], v[52:55]
	v_mfma_f32_16x16x32_bf16 v[56:59], v[226:229], v[174:177], v[56:59]
	v_mfma_f32_16x16x32_bf16 v[36:39], v[218:221], v[194:197], v[36:39]
	v_mfma_f32_16x16x32_bf16 v[40:43], v[226:229], v[194:197], v[40:43]
	v_mfma_f32_16x16x32_bf16 v[20:23], v[218:221], v[202:205], v[20:23]
	v_mfma_f32_16x16x32_bf16 v[24:27], v[226:229], v[202:205], v[24:27]
	v_mfma_f32_16x16x32_bf16 v[8:11], v[218:221], v[210:213], v[8:11]
	v_mfma_f32_16x16x32_bf16 v[4:7], v[226:229], v[210:213], v[4:7]
	v_mfma_f32_16x16x32_bf16 v[52:55], v[222:225], v[190:193], v[52:55]
	v_mfma_f32_16x16x32_bf16 v[56:59], v[230:233], v[190:193], v[56:59]
	v_mfma_f32_16x16x32_bf16 v[36:39], v[222:225], v[198:201], v[36:39]
	v_mfma_f32_16x16x32_bf16 v[40:43], v[230:233], v[198:201], v[40:43]
	v_mfma_f32_16x16x32_bf16 v[20:23], v[222:225], v[206:209], v[20:23]
	v_mfma_f32_16x16x32_bf16 v[24:27], v[230:233], v[206:209], v[24:27]
	v_mfma_f32_16x16x32_bf16 v[8:11], v[222:225], v[214:217], v[8:11]
	v_mfma_f32_16x16x32_bf16 v[4:7], v[230:233], v[214:217], v[4:7]
	s_add_i32 s55, 0, 0x18000
	v_add_u32_e32 v157, s55, v140
	s_barrier
	s_add_u32 s22, s22, 0x80000
	s_addc_u32 s23, s23, 0
	s_mov_b32 m0, s41
	s_nop 0
	global_load_lds_dwordx4 v134, s[22:23]
	s_mov_b32 m0, s42
	s_nop 0
	global_load_lds_dwordx4 v132, s[22:23]
	ds_read_b128 v[144:147], v157
	ds_read_b128 v[162:165], v157 offset:1024
	ds_read_b128 v[166:169], v157 offset:2048
	ds_read_b128 v[170:173], v157 offset:3072
	ds_read_b128 v[174:177], v143 offset:32768
	ds_read_b128 v[190:193], v143 offset:33792
	ds_read_b128 v[194:197], v143 offset:34816
	ds_read_b128 v[198:201], v143 offset:35840
	ds_read_b128 v[202:205], v143 offset:36864
	ds_read_b128 v[206:209], v143 offset:37888
	ds_read_b128 v[210:213], v143 offset:38912
	ds_read_b128 v[214:217], v143 offset:39936
	s_waitcnt lgkmcnt(8)
	s_barrier
	s_waitcnt lgkmcnt(0)
	s_waitcnt lgkmcnt(0)
	v_mfma_f32_16x16x32_bf16 v[124:127], v[144:147], v[174:177], v[124:127]
	v_mfma_f32_16x16x32_bf16 v[128:131], v[166:169], v[174:177], v[128:131]
	v_mfma_f32_16x16x32_bf16 v[108:111], v[144:147], v[194:197], v[108:111]
	v_mfma_f32_16x16x32_bf16 v[112:115], v[166:169], v[194:197], v[112:115]
	v_mfma_f32_16x16x32_bf16 v[92:95], v[144:147], v[202:205], v[92:95]
	v_mfma_f32_16x16x32_bf16 v[96:99], v[166:169], v[202:205], v[96:99]
	v_mfma_f32_16x16x32_bf16 v[76:79], v[144:147], v[210:213], v[76:79]
	v_mfma_f32_16x16x32_bf16 v[80:83], v[166:169], v[210:213], v[80:83]
	v_mfma_f32_16x16x32_bf16 v[124:127], v[162:165], v[190:193], v[124:127]
	v_mfma_f32_16x16x32_bf16 v[128:131], v[170:173], v[190:193], v[128:131]
	v_mfma_f32_16x16x32_bf16 v[108:111], v[162:165], v[198:201], v[108:111]
	v_mfma_f32_16x16x32_bf16 v[112:115], v[170:173], v[198:201], v[112:115]
	v_mfma_f32_16x16x32_bf16 v[92:95], v[162:165], v[206:209], v[92:95]
	v_mfma_f32_16x16x32_bf16 v[96:99], v[170:173], v[206:209], v[96:99]
	v_mfma_f32_16x16x32_bf16 v[76:79], v[162:165], v[214:217], v[76:79]
	v_mfma_f32_16x16x32_bf16 v[80:83], v[170:173], v[214:217], v[80:83]
	s_barrier
	s_add_i32 s22, 0, 0x1c000
	s_add_i32 s23, s55, s38
	v_add_u32_e32 v157, s22, v140
	v_lshl_add_u64 v[178:179], v[178:179], 0, s[30:31]
	s_mov_b32 m0, s23
	s_nop 0
	global_load_lds_dwordx4 v[178:179], off
	v_lshl_add_u64 v[178:179], v[234:235], 0, s[30:31]
	s_add_i32 m0, s23, 0x2000
	s_nop 0
	global_load_lds_dwordx4 v[178:179], off
	ds_read_b128 v[218:221], v157
	ds_read_b128 v[222:225], v157 offset:1024
	ds_read_b128 v[226:229], v157 offset:2048
	ds_read_b128 v[230:233], v157 offset:3072
	s_barrier
	s_waitcnt lgkmcnt(0)
	s_waitcnt lgkmcnt(0)
	v_mfma_f32_16x16x32_bf16 v[116:119], v[218:221], v[174:177], v[116:119]
	v_mfma_f32_16x16x32_bf16 v[120:123], v[226:229], v[174:177], v[120:123]
	v_mfma_f32_16x16x32_bf16 v[100:103], v[218:221], v[194:197], v[100:103]
	v_mfma_f32_16x16x32_bf16 v[104:107], v[226:229], v[194:197], v[104:107]
	v_mfma_f32_16x16x32_bf16 v[84:87], v[218:221], v[202:205], v[84:87]
	v_mfma_f32_16x16x32_bf16 v[88:91], v[226:229], v[202:205], v[88:91]
	v_mfma_f32_16x16x32_bf16 v[68:71], v[218:221], v[210:213], v[68:71]
	v_mfma_f32_16x16x32_bf16 v[72:75], v[226:229], v[210:213], v[72:75]
	v_mfma_f32_16x16x32_bf16 v[116:119], v[222:225], v[190:193], v[116:119]
	v_mfma_f32_16x16x32_bf16 v[120:123], v[230:233], v[190:193], v[120:123]
	v_mfma_f32_16x16x32_bf16 v[100:103], v[222:225], v[198:201], v[100:103]
	v_mfma_f32_16x16x32_bf16 v[104:107], v[230:233], v[198:201], v[104:107]
	v_mfma_f32_16x16x32_bf16 v[84:87], v[222:225], v[206:209], v[84:87]
	v_mfma_f32_16x16x32_bf16 v[88:91], v[230:233], v[206:209], v[88:91]
	v_mfma_f32_16x16x32_bf16 v[68:71], v[222:225], v[214:217], v[68:71]
	v_mfma_f32_16x16x32_bf16 v[72:75], v[230:233], v[214:217], v[72:75]
	s_mov_b32 m0, s43
	v_lshl_add_u64 v[178:179], v[236:237], 0, s[30:31]
	s_barrier
	global_load_lds_dwordx4 v[178:179], off
	v_lshl_add_u64 v[178:179], v[238:239], 0, s[30:31]
	s_mov_b32 m0, s46
	s_nop 0
	global_load_lds_dwordx4 v[178:179], off
	ds_read_b128 v[174:177], v143 offset:49152
	ds_read_b128 v[190:193], v143 offset:50176
	ds_read_b128 v[194:197], v143 offset:51200
	ds_read_b128 v[198:201], v143 offset:52224
	ds_read_b128 v[202:205], v143 offset:53248
	ds_read_b128 v[206:209], v143 offset:54272
	ds_read_b128 v[210:213], v143 offset:55296
	ds_read_b128 v[214:217], v143 offset:56320
	s_barrier
; #define PG8_STAGE(bufoff, gbase, voff) do { _Pragma("unroll") for (int _i = 0; _i < 2; ++_i) \
;         __builtin_amdgcn_global_load_lds((const unsigned*)((const char*)(gbase) + (voff)[_i]), (LAS unsigned*)(lds + (bufoff) + ldsw + _i * 8192), 16, 0, 0); } while (0)
; #define PG8_WAIT_V(n) asm volatile("s_waitcnt vmcnt(" #n ")" ::: "memory")
; #define PG8_WAIT_L(n) asm volatile("s_waitcnt lgkmcnt(" #n ")" ::: "memory")
; #define PG8_BAR __builtin_amdgcn_s_barrier()
; #define PG8_SCHED __builtin_amdgcn_sched_barrier(0)
; template <class Epi>
; __device__ __forceinline__ void gemm_phase(LAS unsigned char* lds, const Gemm g, const StaticOrder& S, const Epi& E, const int tid) {
;     ...
;             PG8_BAR; PG8_WAIT_L(0); PG8_MMA(1, 0, At, B0); PG8_BAR; PG8_SCHED;
;             PG8_STAGE(PG8_SB(1, 1), b3 + hstepB, voffB);
;             PG8_WAIT_V(6); PG8_BAR; PG8_MMA(1, 1, At, B1); PG8_BAR;
;     __device__ __forceinline__ void operator()(f32x4 (&acc)[2][2][4][2], const pg8::Unit& u, int wr, int wc, int fr, int fq) const {
;         const bool hi = fr >= 8;
;         const int row0 = u.pm * 256 + wr * 64 + (fr & 7), col = u.pn * 256 + wc * 64 + fq * 8 + (hi ? 32 : 0);
; #pragma unroll
;         for (int ai = 0; ai < 2; ++ai)
; #pragma unroll
;             for (int m = 0; m < 4; ++m) {
;                 const h8 x0 = pack8(acc[ai][0][m][0], acc[ai][0][m][1]), x1 = pack8(acc[ai][1][m][0], acc[ai][1][m][1]);
;                 const i32x4 snd = hi ? __builtin_bit_cast(i32x4, x0) : __builtin_bit_cast(i32x4, x1);
;                 i32x4 rcv;
; #pragma unroll
;                 for (int d = 0; d < 4; ++d) rcv[d] = __builtin_amdgcn_update_dpp(0, snd[d], 0x128  , 0xF, 0xF, false);
;                 const h8 rv = __builtin_bit_cast(h8, rcv);
;                 const h8 vA = hi ? rv : x0;
;                 const h8 vB = hi ? x1 : rv;
;                 half_t* rowp = O + (size_t)(row0 + ai * 128 + m * 16) * NIN + col;
;                 __builtin_nontemporal_store(vA, (h8*)rowp); __builtin_nontemporal_store(vB, (h8*)(rowp + (size_t)8 * NIN)); }
	s_waitcnt lgkmcnt(0)
	s_waitcnt lgkmcnt(0)
	v_mfma_f32_16x16x32_bf16 v[60:63], v[144:147], v[174:177], v[60:63]
	v_mfma_f32_16x16x32_bf16 v[64:67], v[166:169], v[174:177], v[64:67]
	v_mfma_f32_16x16x32_bf16 v[44:47], v[144:147], v[194:197], v[44:47]
	v_mfma_f32_16x16x32_bf16 v[48:51], v[166:169], v[194:197], v[48:51]
	v_mfma_f32_16x16x32_bf16 v[28:31], v[144:147], v[202:205], v[28:31]
	v_mfma_f32_16x16x32_bf16 v[32:35], v[166:169], v[202:205], v[32:35]
	v_mfma_f32_16x16x32_bf16 v[12:15], v[144:147], v[210:213], v[12:15]
	v_mfma_f32_16x16x32_bf16 v[16:19], v[166:169], v[210:213], v[16:19]
	v_mfma_f32_16x16x32_bf16 v[60:63], v[162:165], v[190:193], v[60:63]
	v_mfma_f32_16x16x32_bf16 v[64:67], v[170:173], v[190:193], v[64:67]
	v_mfma_f32_16x16x32_bf16 v[44:47], v[162:165], v[198:201], v[44:47]
	v_mfma_f32_16x16x32_bf16 v[48:51], v[170:173], v[198:201], v[48:51]
	v_mfma_f32_16x16x32_bf16 v[28:31], v[162:165], v[206:209], v[28:31]
	v_mfma_f32_16x16x32_bf16 v[32:35], v[170:173], v[206:209], v[32:35]
	v_mfma_f32_16x16x32_bf16 v[12:15], v[162:165], v[214:217], v[12:15]
	v_mfma_f32_16x16x32_bf16 v[16:19], v[170:173], v[214:217], v[16:19]
	s_barrier
	s_add_u32 s18, s18, 0x20080
	s_addc_u32 s19, s19, 0
	s_add_i32 s22, s22, s38
	s_mov_b32 m0, s22
	s_nop 0
	global_load_lds_dwordx4 v2, s[18:19]
	v_lshl_add_u64 v[144:145], s[18:19], 0, v[0:1]
	s_add_i32 m0, s22, 0x2000
	s_nop 0
	global_load_lds_dwordx4 v[144:145], off
	s_waitcnt vmcnt(6)
	s_barrier
	v_mfma_f32_16x16x32_bf16 v[52:55], v[218:221], v[174:177], v[52:55]
	v_mfma_f32_16x16x32_bf16 v[56:59], v[226:229], v[174:177], v[56:59]
	v_mfma_f32_16x16x32_bf16 v[36:39], v[218:221], v[194:197], v[36:39]
	v_mfma_f32_16x16x32_bf16 v[40:43], v[226:229], v[194:197], v[40:43]
	v_mfma_f32_16x16x32_bf16 v[20:23], v[218:221], v[202:205], v[20:23]
	v_mfma_f32_16x16x32_bf16 v[24:27], v[226:229], v[202:205], v[24:27]
	v_mfma_f32_16x16x32_bf16 v[8:11], v[218:221], v[210:213], v[8:11]
	v_mfma_f32_16x16x32_bf16 v[4:7], v[226:229], v[210:213], v[4:7]
	v_mfma_f32_16x16x32_bf16 v[52:55], v[222:225], v[190:193], v[52:55]
	v_mfma_f32_16x16x32_bf16 v[56:59], v[230:233], v[190:193], v[56:59]
	v_mfma_f32_16x16x32_bf16 v[36:39], v[222:225], v[198:201], v[36:39]
	v_mfma_f32_16x16x32_bf16 v[40:43], v[230:233], v[198:201], v[40:43]
	v_mfma_f32_16x16x32_bf16 v[20:23], v[222:225], v[206:209], v[20:23]
	v_mfma_f32_16x16x32_bf16 v[24:27], v[230:233], v[206:209], v[24:27]
	v_mfma_f32_16x16x32_bf16 v[8:11], v[222:225], v[214:217], v[8:11]
	v_mfma_f32_16x16x32_bf16 v[4:7], v[230:233], v[214:217], v[4:7]
	s_add_i32 s54, s54, 2
	s_add_u32 s14, s14, 0x100
	s_addc_u32 s15, s15, 0
	s_add_u32 s52, s52, 0x100
	s_addc_u32 s53, s53, 0
	s_cmp_gt_u32 s54, 29
	s_barrier
	s_cbranch_scc0 .LBB0_332
	v_cvt_pk_f16_f32 v124, v124, v125
	v_cvt_pk_f16_f32 v116, v116, v117
	v_cvt_pk_f16_f32 v130, v130, v131
	v_cvt_pk_f16_f32 v131, v122, v123
	v_cvt_pk_f16_f32 v128, v128, v129
	v_cvt_pk_f16_f32 v129, v120, v121
	v_cvt_pk_f16_f32 v121, v126, v127
	v_cvt_pk_f16_f32 v118, v118, v119
	v_cndmask_b32_e64 v117, v116, v124, s[4:5]
	v_mov_b32_e32 v147, v3
	v_cndmask_b32_e64 v122, v131, v130, s[4:5]
	v_cndmask_b32_e64 v119, v118, v121, s[4:5]
	v_mov_b32_dpp v147, v117 row_ror:8 row_mask:0xf bank_mask:0xf
	v_mov_b32_e32 v117, v3
	v_mov_b32_e32 v125, v3
	v_lshl_or_b32 v144, s48, 8, v142
	v_cndmask_b32_e64 v120, v129, v128, s[4:5]
	v_mov_b32_dpp v117, v119 row_ror:8 row_mask:0xf bank_mask:0xf
	v_mov_b32_e32 v119, v3
	v_mov_b32_dpp v125, v122 row_ror:8 row_mask:0xf bank_mask:0xf
	v_lshl_add_u32 v146, s49, 8, v141
	v_ashrrev_i32_e32 v145, 31, v144
	v_mov_b32_dpp v119, v120 row_ror:8 row_mask:0xf bank_mask:0xf
	v_cndmask_b32_e64 v123, v130, v125, s[4:5]
	v_cndmask_b32_e64 v121, v121, v117, s[4:5]
	v_cndmask_b32_e64 v120, v124, v147, s[4:5]
	v_cndmask_b32_e64 v127, v125, v131, s[4:5]
	v_cndmask_b32_e64 v125, v117, v118, s[4:5]
	v_cndmask_b32_e64 v124, v147, v116, s[4:5]
	v_mov_b64_e32 v[116:117], s[36:37]
	v_cndmask_b32_e64 v122, v128, v119, s[4:5]
	v_cndmask_b32_e64 v126, v119, v129, s[4:5]
	v_mad_i64_i32 v[128:129], s[14:15], v146, s35, v[116:117]
	v_lshlrev_b64 v[118:119], 1, v[144:145]
	v_lshl_add_u64 v[128:129], v[128:129], 0, v[118:119]
	s_mov_b32 s1, 0x3c000
	global_store_dwordx4 v[128:129], v[120:123], off nt
	v_cvt_pk_f16_f32 v112, v112, v113
	v_cvt_pk_f16_f32 v104, v104, v105
	v_add_co_u32_e32 v120, vcc, s1, v128
	v_cvt_pk_f16_f32 v108, v108, v109
	s_nop 0
	v_addc_co_u32_e32 v121, vcc, 0, v129, vcc
	v_cvt_pk_f16_f32 v109, v100, v101
	global_store_dwordx4 v[120:121], v[124:127], off nt
	v_cvt_pk_f16_f32 v114, v114, v115
	v_cvt_pk_f16_f32 v106, v106, v107
	v_cndmask_b32_e64 v105, v104, v112, s[4:5]
	v_cndmask_b32_e64 v100, v109, v108, s[4:5]
	v_mov_b32_e32 v113, v3
	v_mov_b32_e32 v120, v3
	v_cndmask_b32_e64 v107, v106, v114, s[4:5]
	v_cvt_pk_f16_f32 v110, v110, v111
	v_cvt_pk_f16_f32 v111, v102, v103
	v_mov_b32_dpp v113, v100 row_ror:8 row_mask:0xf bank_mask:0xf
	v_mov_b32_dpp v120, v105 row_ror:8 row_mask:0xf bank_mask:0xf
	v_mov_b32_e32 v105, v3
	v_cndmask_b32_e64 v102, v111, v110, s[4:5]
	v_mov_b32_e32 v115, v3
	v_mov_b32_dpp v105, v107 row_ror:8 row_mask:0xf bank_mask:0xf
	v_cndmask_b32_e64 v100, v108, v113, s[4:5]
	v_or_b32_e32 v108, 16, v146
	v_mov_b32_dpp v115, v102 row_ror:8 row_mask:0xf bank_mask:0xf
	v_cndmask_b32_e64 v107, v105, v106, s[4:5]
	v_cndmask_b32_e64 v106, v120, v104, s[4:5]
	v_cndmask_b32_e64 v104, v113, v109, s[4:5]
	v_mad_i64_i32 v[108:109], s[14:15], v108, s35, v[116:117]
	v_cndmask_b32_e64 v103, v114, v105, s[4:5]
	v_cndmask_b32_e64 v102, v112, v120, s[4:5]
	v_cndmask_b32_e64 v101, v110, v115, s[4:5]
	v_lshl_add_u64 v[108:109], v[108:109], 0, v[118:119]
;     __device__ __forceinline__ void operator()(f32x4 (&acc)[2][2][4][2], const pg8::Unit& u, int wr, int wc, int fr, int fq) const {
;         const bool hi = fr >= 8;
;         const int row0 = u.pm * 256 + wr * 64 + (fr & 7), col = u.pn * 256 + wc * 64 + fq * 8 + (hi ? 32 : 0);
; #pragma unroll
;         for (int ai = 0; ai < 2; ++ai)
; #pragma unroll
;             for (int m = 0; m < 4; ++m) {
;                 const h8 x0 = pack8(acc[ai][0][m][0], acc[ai][0][m][1]), x1 = pack8(acc[ai][1][m][0], acc[ai][1][m][1]);
;                 const i32x4 snd = hi ? __builtin_bit_cast(i32x4, x0) : __builtin_bit_cast(i32x4, x1);
;                 i32x4 rcv;
; #pragma unroll
;                 for (int d = 0; d < 4; ++d) rcv[d] = __builtin_amdgcn_update_dpp(0, snd[d], 0x128  , 0xF, 0xF, false);
;                 const h8 rv = __builtin_bit_cast(h8, rcv);
;                 const h8 vA = hi ? rv : x0;
;                 const h8 vB = hi ? x1 : rv;
;                 half_t* rowp = O + (size_t)(row0 + ai * 128 + m * 16) * NIN + col;
;                 __builtin_nontemporal_store(vA, (h8*)rowp); __builtin_nontemporal_store(vB, (h8*)(rowp + (size_t)8 * NIN)); }
	global_store_dwordx4 v[108:109], v[100:103], off nt
	v_cndmask_b32_e64 v105, v115, v111, s[4:5]
	v_cvt_pk_f16_f32 v96, v96, v97
	v_add_co_u32_e32 v100, vcc, s1, v108
	v_cvt_pk_f16_f32 v88, v88, v89
	s_nop 0
	v_addc_co_u32_e32 v101, vcc, 0, v109, vcc
	v_cvt_pk_f16_f32 v92, v92, v93
	v_cvt_pk_f16_f32 v93, v84, v85
	global_store_dwordx4 v[100:101], v[104:107], off nt
	v_cvt_pk_f16_f32 v98, v98, v99
	v_cvt_pk_f16_f32 v90, v90, v91
	v_cndmask_b32_e64 v89, v88, v96, s[4:5]
	v_cndmask_b32_e64 v84, v93, v92, s[4:5]
	v_mov_b32_e32 v97, v3
	v_mov_b32_e32 v100, v3
	v_cndmask_b32_e64 v91, v90, v98, s[4:5]
	v_cvt_pk_f16_f32 v94, v94, v95
	v_cvt_pk_f16_f32 v95, v86, v87
	v_mov_b32_dpp v97, v84 row_ror:8 row_mask:0xf bank_mask:0xf
	v_mov_b32_dpp v100, v89 row_ror:8 row_mask:0xf bank_mask:0xf
	v_mov_b32_e32 v89, v3
	v_cndmask_b32_e64 v86, v95, v94, s[4:5]
	v_mov_b32_e32 v99, v3
	v_mov_b32_dpp v89, v91 row_ror:8 row_mask:0xf bank_mask:0xf
	v_cndmask_b32_e64 v84, v92, v97, s[4:5]
	v_or_b32_e32 v92, 32, v146
	v_mov_b32_dpp v99, v86 row_ror:8 row_mask:0xf bank_mask:0xf
	v_cndmask_b32_e64 v91, v89, v90, s[4:5]
	v_cndmask_b32_e64 v90, v100, v88, s[4:5]
	v_cndmask_b32_e64 v88, v97, v93, s[4:5]
	v_mad_i64_i32 v[92:93], s[14:15], v92, s35, v[116:117]
	v_cndmask_b32_e64 v87, v98, v89, s[4:5]
	v_cndmask_b32_e64 v86, v96, v100, s[4:5]
	v_cndmask_b32_e64 v85, v94, v99, s[4:5]
	v_lshl_add_u64 v[92:93], v[92:93], 0, v[118:119]
	global_store_dwordx4 v[92:93], v[84:87], off nt
	v_cndmask_b32_e64 v89, v99, v95, s[4:5]
	v_cvt_pk_f16_f32 v80, v80, v81
	v_add_co_u32_e32 v84, vcc, s1, v92
	v_cvt_pk_f16_f32 v72, v72, v73
	s_nop 0
	v_addc_co_u32_e32 v85, vcc, 0, v93, vcc
	v_cvt_pk_f16_f32 v76, v76, v77
	v_cvt_pk_f16_f32 v77, v68, v69
	global_store_dwordx4 v[84:85], v[88:91], off nt
	v_cvt_pk_f16_f32 v82, v82, v83
	v_cvt_pk_f16_f32 v74, v74, v75
	v_cndmask_b32_e64 v73, v72, v80, s[4:5]
	v_cndmask_b32_e64 v68, v77, v76, s[4:5]
	v_mov_b32_e32 v81, v3
	v_mov_b32_e32 v84, v3
	v_cndmask_b32_e64 v75, v74, v82, s[4:5]
	v_cvt_pk_f16_f32 v78, v78, v79
	v_cvt_pk_f16_f32 v79, v70, v71
	v_mov_b32_dpp v81, v68 row_ror:8 row_mask:0xf bank_mask:0xf
	v_mov_b32_dpp v84, v73 row_ror:8 row_mask:0xf bank_mask:0xf
	v_mov_b32_e32 v73, v3
	v_cndmask_b32_e64 v70, v79, v78, s[4:5]
	v_mov_b32_e32 v83, v3
	v_mov_b32_dpp v73, v75 row_ror:8 row_mask:0xf bank_mask:0xf
	v_cndmask_b32_e64 v68, v76, v81, s[4:5]
	v_or_b32_e32 v76, 48, v146
	v_mov_b32_dpp v83, v70 row_ror:8 row_mask:0xf bank_mask:0xf
	v_cndmask_b32_e64 v75, v73, v74, s[4:5]
	v_cndmask_b32_e64 v74, v84, v72, s[4:5]
	v_cndmask_b32_e64 v72, v81, v77, s[4:5]
	v_mad_i64_i32 v[76:77], s[14:15], v76, s35, v[116:117]
	v_cndmask_b32_e64 v71, v82, v73, s[4:5]
	v_cndmask_b32_e64 v70, v80, v84, s[4:5]
	v_cndmask_b32_e64 v69, v78, v83, s[4:5]
	v_lshl_add_u64 v[76:77], v[76:77], 0, v[118:119]
	global_store_dwordx4 v[76:77], v[68:71], off nt
	v_cndmask_b32_e64 v73, v83, v79, s[4:5]
	v_cvt_pk_f16_f32 v64, v64, v65
	v_add_co_u32_e32 v68, vcc, s1, v76
	v_cvt_pk_f16_f32 v56, v56, v57
	s_nop 0
	v_addc_co_u32_e32 v69, vcc, 0, v77, vcc
	global_store_dwordx4 v[68:69], v[72:75], off nt
	v_cvt_pk_f16_f32 v66, v66, v67
	v_cvt_pk_f16_f32 v58, v58, v59
	v_cndmask_b32_e64 v57, v56, v64, s[4:5]
	v_cvt_pk_f16_f32 v60, v60, v61
	v_cvt_pk_f16_f32 v61, v52, v53
	v_mov_b32_e32 v69, v3
	v_cndmask_b32_e64 v59, v58, v66, s[4:5]
	v_cvt_pk_f16_f32 v62, v62, v63
	v_cvt_pk_f16_f32 v63, v54, v55
	v_cndmask_b32_e64 v52, v61, v60, s[4:5]
	v_mov_b32_e32 v65, v3
	v_mov_b32_dpp v69, v57 row_ror:8 row_mask:0xf bank_mask:0xf
	v_mov_b32_e32 v57, v3
	v_add_u32_e32 v68, 0x80, v146
	v_cndmask_b32_e64 v54, v63, v62, s[4:5]
	v_mov_b32_dpp v65, v52 row_ror:8 row_mask:0xf bank_mask:0xf
	v_mov_b32_e32 v67, v3
	v_mov_b32_dpp v57, v59 row_ror:8 row_mask:0xf bank_mask:0xf
	v_cndmask_b32_e64 v52, v60, v65, s[4:5]
	v_mov_b32_dpp v67, v54 row_ror:8 row_mask:0xf bank_mask:0xf
	v_cndmask_b32_e64 v59, v57, v58, s[4:5]
	v_cndmask_b32_e64 v58, v69, v56, s[4:5]
	v_cndmask_b32_e64 v56, v65, v61, s[4:5]
	v_mad_i64_i32 v[60:61], s[14:15], v68, s35, v[116:117]
	v_cndmask_b32_e64 v55, v66, v57, s[4:5]
	v_cndmask_b32_e64 v54, v64, v69, s[4:5]
	v_cndmask_b32_e64 v53, v62, v67, s[4:5]
	v_lshl_add_u64 v[60:61], v[60:61], 0, v[118:119]
	global_store_dwordx4 v[60:61], v[52:55], off nt
	v_cndmask_b32_e64 v57, v67, v63, s[4:5]
	v_cvt_pk_f16_f32 v48, v48, v49
	v_add_co_u32_e32 v52, vcc, s1, v60
	v_cvt_pk_f16_f32 v40, v40, v41
	s_nop 0
	v_addc_co_u32_e32 v53, vcc, 0, v61, vcc
	v_cvt_pk_f16_f32 v44, v44, v45
	v_cvt_pk_f16_f32 v45, v36, v37
; #define PG8_WAIT_V(n) asm volatile("s_waitcnt vmcnt(" #n ")" ::: "memory")
; #define PG8_BAR __builtin_amdgcn_s_barrier()
; template <class Epi>
; __device__ __forceinline__ void gemm_phase(LAS unsigned char* lds, const Gemm g, const StaticOrder& S, const Epi& E, const int tid) {
;     ...
;         if (!has_next) break;
; #pragma unroll
;         for (int a = 0; a < 2; ++a)
; #pragma unroll
;             for (int b = 0; b < 2; ++b)
; #pragma unroll
;                 for (int m = 0; m < 4; ++m)
; #pragma unroll
;                     for (int n = 0; n < 2; ++n) acc[a][b][m][n] = (f32x4){0.f, 0.f, 0.f, 0.f};
;         cur = nxt; cA = nA; cB = nB; ++ui;
;     }
;     PG8_WAIT_V(0);
;     if (wr == 0) PG8_BAR;
;     PG8_BAR;
;     __device__ __forceinline__ void operator()(f32x4 (&acc)[2][2][4][2], const pg8::Unit& u, int wr, int wc, int fr, int fq) const {
;         const bool hi = fr >= 8;
;         const int row0 = u.pm * 256 + wr * 64 + (fr & 7), col = u.pn * 256 + wc * 64 + fq * 8 + (hi ? 32 : 0);
; #pragma unroll
;         for (int ai = 0; ai < 2; ++ai)
; #pragma unroll
;             for (int m = 0; m < 4; ++m) {
;                 const h8 x0 = pack8(acc[ai][0][m][0], acc[ai][0][m][1]), x1 = pack8(acc[ai][1][m][0], acc[ai][1][m][1]);
;                 const i32x4 snd = hi ? __builtin_bit_cast(i32x4, x0) : __builtin_bit_cast(i32x4, x1);
;                 i32x4 rcv;
; #pragma unroll
;                 for (int d = 0; d < 4; ++d) rcv[d] = __builtin_amdgcn_update_dpp(0, snd[d], 0x128  , 0xF, 0xF, false);
;                 const h8 rv = __builtin_bit_cast(h8, rcv);
;                 const h8 vA = hi ? rv : x0;
;                 const h8 vB = hi ? x1 : rv;
;                 half_t* rowp = O + (size_t)(row0 + ai * 128 + m * 16) * NIN + col;
;                 __builtin_nontemporal_store(vA, (h8*)rowp); __builtin_nontemporal_store(vB, (h8*)(rowp + (size_t)8 * NIN)); }
	global_store_dwordx4 v[52:53], v[56:59], off nt
	v_cvt_pk_f16_f32 v50, v50, v51
	v_cvt_pk_f16_f32 v42, v42, v43
	v_cndmask_b32_e64 v41, v40, v48, s[4:5]
	v_cndmask_b32_e64 v36, v45, v44, s[4:5]
	v_mov_b32_e32 v49, v3
	v_mov_b32_e32 v52, v3
	v_cndmask_b32_e64 v43, v42, v50, s[4:5]
	v_cvt_pk_f16_f32 v46, v46, v47
	v_cvt_pk_f16_f32 v47, v38, v39
	v_mov_b32_dpp v49, v36 row_ror:8 row_mask:0xf bank_mask:0xf
	v_mov_b32_dpp v52, v41 row_ror:8 row_mask:0xf bank_mask:0xf
	v_mov_b32_e32 v41, v3
	v_cndmask_b32_e64 v38, v47, v46, s[4:5]
	v_mov_b32_e32 v51, v3
	v_mov_b32_dpp v41, v43 row_ror:8 row_mask:0xf bank_mask:0xf
	v_cndmask_b32_e64 v36, v44, v49, s[4:5]
	v_add_u32_e32 v44, 0x90, v146
	v_mov_b32_dpp v51, v38 row_ror:8 row_mask:0xf bank_mask:0xf
	v_cndmask_b32_e64 v43, v41, v42, s[4:5]
	v_cndmask_b32_e64 v42, v52, v40, s[4:5]
	v_cndmask_b32_e64 v40, v49, v45, s[4:5]
	v_mad_i64_i32 v[44:45], s[14:15], v44, s35, v[116:117]
	v_cndmask_b32_e64 v39, v50, v41, s[4:5]
	v_cndmask_b32_e64 v38, v48, v52, s[4:5]
	v_cndmask_b32_e64 v37, v46, v51, s[4:5]
	v_lshl_add_u64 v[44:45], v[44:45], 0, v[118:119]
	global_store_dwordx4 v[44:45], v[36:39], off nt
	v_cndmask_b32_e64 v41, v51, v47, s[4:5]
	v_cvt_pk_f16_f32 v32, v32, v33
	v_add_co_u32_e32 v36, vcc, s1, v44
	v_cvt_pk_f16_f32 v24, v24, v25
	s_nop 0
	v_addc_co_u32_e32 v37, vcc, 0, v45, vcc
	v_cvt_pk_f16_f32 v28, v28, v29
	v_cvt_pk_f16_f32 v29, v20, v21
	global_store_dwordx4 v[36:37], v[40:43], off nt
	v_cvt_pk_f16_f32 v34, v34, v35
	v_cvt_pk_f16_f32 v26, v26, v27
	v_cndmask_b32_e64 v25, v24, v32, s[4:5]
	v_cndmask_b32_e64 v20, v29, v28, s[4:5]
	v_mov_b32_e32 v33, v3
	v_mov_b32_e32 v36, v3
	v_cndmask_b32_e64 v27, v26, v34, s[4:5]
	v_cvt_pk_f16_f32 v30, v30, v31
	v_cvt_pk_f16_f32 v31, v22, v23
	v_mov_b32_dpp v33, v20 row_ror:8 row_mask:0xf bank_mask:0xf
	v_mov_b32_dpp v36, v25 row_ror:8 row_mask:0xf bank_mask:0xf
	v_mov_b32_e32 v25, v3
	v_cvt_pk_f16_f32 v16, v16, v17
	v_cvt_pk_f16_f32 v17, v4, v5
	v_cvt_pk_f16_f32 v5, v14, v15
	v_cvt_pk_f16_f32 v14, v10, v11
	v_cvt_pk_f16_f32 v10, v12, v13
	v_cvt_pk_f16_f32 v8, v8, v9
	v_cndmask_b32_e64 v22, v31, v30, s[4:5]
	v_mov_b32_e32 v35, v3
	v_mov_b32_dpp v25, v27 row_ror:8 row_mask:0xf bank_mask:0xf
	v_cndmask_b32_e64 v20, v28, v33, s[4:5]
	v_add_u32_e32 v28, 0xa0, v146
	v_cndmask_b32_e64 v9, v8, v10, s[4:5]
	v_mov_b32_e32 v12, v3
	v_mov_b32_dpp v35, v22 row_ror:8 row_mask:0xf bank_mask:0xf
	v_cndmask_b32_e64 v27, v25, v26, s[4:5]
	v_cndmask_b32_e64 v26, v36, v24, s[4:5]
	v_cndmask_b32_e64 v24, v33, v29, s[4:5]
	v_mad_i64_i32 v[28:29], s[14:15], v28, s35, v[116:117]
	v_cvt_pk_f16_f32 v18, v18, v19
	v_cvt_pk_f16_f32 v19, v6, v7
	v_cndmask_b32_e64 v4, v17, v16, s[4:5]
	v_mov_b32_dpp v12, v9 row_ror:8 row_mask:0xf bank_mask:0xf
	v_mov_b32_e32 v13, v3
	v_cndmask_b32_e64 v23, v34, v25, s[4:5]
	v_cndmask_b32_e64 v22, v32, v36, s[4:5]
	v_cndmask_b32_e64 v21, v30, v35, s[4:5]
	v_lshl_add_u64 v[28:29], v[28:29], 0, v[118:119]
	v_cndmask_b32_e64 v6, v19, v18, s[4:5]
	v_cndmask_b32_e64 v7, v14, v5, s[4:5]
	v_mov_b32_e32 v9, v3
	v_mov_b32_dpp v13, v4 row_ror:8 row_mask:0xf bank_mask:0xf
	v_mov_b32_e32 v11, v3
	v_cndmask_b32_e64 v4, v10, v12, s[4:5]
	v_cndmask_b32_e64 v8, v12, v8, s[4:5]
	v_add_u32_e32 v12, 0xb0, v146
	global_store_dwordx4 v[28:29], v[20:23], off nt
	v_mov_b32_dpp v9, v7 row_ror:8 row_mask:0xf bank_mask:0xf
	v_mov_b32_dpp v11, v6 row_ror:8 row_mask:0xf bank_mask:0xf
	v_add_co_u32_e32 v20, vcc, s1, v28
	v_cndmask_b32_e64 v6, v16, v13, s[4:5]
	v_cndmask_b32_e64 v10, v13, v17, s[4:5]
	v_mad_i64_i32 v[12:13], s[14:15], v12, s35, v[116:117]
	v_addc_co_u32_e32 v21, vcc, 0, v29, vcc
	v_cndmask_b32_e64 v7, v18, v11, s[4:5]
	v_cndmask_b32_e64 v5, v5, v9, s[4:5]
	v_lshl_add_u64 v[12:13], v[12:13], 0, v[118:119]
	global_store_dwordx4 v[12:13], v[4:7], off nt
	v_cndmask_b32_e64 v25, v35, v31, s[4:5]
	v_cndmask_b32_e64 v11, v11, v19, s[4:5]
	v_add_co_u32_e32 v4, vcc, 0x3c000, v12
	v_cndmask_b32_e64 v9, v9, v14, s[4:5]
	s_nop 0
	v_addc_co_u32_e32 v5, vcc, 0, v13, vcc
	s_and_b64 vcc, exec, s[6:7]
	s_mov_b32 s48, s0
	s_mov_b32 s49, s8
	s_mov_b64 s[18:19], s[12:13]
	s_mov_b64 s[14:15], s[10:11]
	global_store_dwordx4 v[20:21], v[24:27], off nt
	global_store_dwordx4 v[4:5], v[8:11], off nt
	s_cbranch_vccz .LBB0_329
	s_waitcnt vmcnt(0)
	v_readlane_b32 s42, v251, 7
	v_readlane_b32 s46, v251, 9
	v_readlane_b32 s48, v251, 13
	s_cmpk_gt_u32 s20, 0xff
	v_readlane_b32 s43, v251, 8
	v_readlane_b32 s47, v251, 10
	v_readlane_b32 s49, v251, 14
	s_cbranch_scc1 .LBB0_336
	s_barrier
